# attention unit preambles: removed serialized vmcnt(0) waits between Q / first K-V tile loads (MLA) and before Q loads (attn64)
# speedup vs baseline: 1.0175x; 1.0011x over previous
; #define LAS __attribute__((address_space(3)))
; template <int DQ>
; __device__ __forceinline__ void attn_unit(LAS unsigned char* lds, const AttnDesc& A, int tid_in, int wid, int lane_in) {
;     constexpr int KSTR = (DQ + 8) * 2, NS = DQ / 16;
;     int tid = tid_in; asm volatile("" : "+v"(tid));
;     const int lane = tid & 63; (void)lane_in;
;     const int r32 = lane & 31, h = lane >> 5;
;     const int nt = A.nloc + 4;
;     bf16x8 qf[NS];
; #pragma unroll
;     for (int s = 0; s < NS; ++s) qf[s] = *(const bf16x8*)(A.q + (size_t)r32 * A.ldq + 16 * s + 8 * h);
;     f32x16 o0, o1;
; #pragma unroll
;     for (int r = 0; r < 16; ++r) { o0[r] = 0.f; o1[r] = 0.f; }
;     float mrun = -1e30f, lrun = 0.f;
;     f32x16 zero16;
; #pragma unroll
;     for (int r = 0; r < 16; ++r) zero16[r] = 0.f;
;     asm volatile("" : "+v"(zero16));
;     const int skey = tid >> 3, sch = tid & 7;
;     u32x4 kreg, vreg, krreg = (u32x4){0u, 0u, 0u, 0u};
;     {
;         const int row0 = (0 < A.nloc) ? A.loc_row0 : A.ctx_row0;
;         kreg = *(const u32x4*)(A.k + (size_t)(row0 + skey) * A.ldk + 8 * sch);
;         vreg = *(const u32x4*)(A.v + (size_t)(row0 + skey) * A.ldv + 8 * sch);
;         if (DQ == 96 && tid < 256) krreg = *(const u32x4*)(A.kr + (size_t)(row0 + (tid >> 2)) * A.ldkr + 8 * (tid & 3));
;     }
;     const LAS float* rpbl = (const LAS float*)(lds + ATT_RPB);
;     const int vtr_off = ((lane & 15) >> 2) * 64 + (16 * ((lane >> 4) & 1) + 4 * (lane & 3)) * 2 + 4 * h * 64;
;     ...
;             if (loc && A.mode == 1) {
;                 const int qc = 32 * (wid & 1) + r32;
;                 const int w0 = min(max(qc - 8, 0), 48);
;                 const int rbase = (A.a0 + t - A.a1 + 7) * 31;
; #pragma unroll
;                 for (int r = 0; r < 16; ++r) {
;                     const int kc = (r & 3) + 8 * (r >> 2) + 4 * h;
;                     { const int dc = min(max(kc - qc + 15, 0), 30); const bool ok = (unsigned)(kc - w0) < 16u; const float bv = rpbl[rbase + dc]; s0[r] = ok ? s0[r] + bv : -1e30f; }
;                     { const int kc2 = kc + 32; const int dc = min(max(kc2 - qc + 15, 0), 30); const bool ok = (unsigned)(kc2 - w0) < 16u; const float bv = rpbl[rbase + dc]; s1[r] = ok ? s1[r] + bv : -1e30f; }
.LBB0_54:
	v_mov_b32_e32 v32, v154
	v_mov_b32_e32 v157, v1
	v_and_b32_e32 v165, 31, v32
	v_mul_u32_u24_e32 v0, s40, v165
	v_bfe_u32 v33, v32, 5, 1
	v_lshlrev_b32_e32 v0, 1, v0
	v_lshl_add_u64 v[2:3], s[0:1], 0, v[0:1]
	v_lshlrev_b32_e32 v156, 4, v33
	v_lshl_add_u64 v[2:3], v[2:3], 0, v[156:157]
	flat_load_dwordx4 v[130:133], v[2:3]
	flat_load_dwordx4 v[134:137], v[2:3] offset:32
	flat_load_dwordx4 v[138:141], v[2:3] offset:64
	flat_load_dwordx4 v[142:145], v[2:3] offset:96
	v_mov_b32_e32 v14, v1
	v_mov_b32_e32 v15, v1
	v_mov_b32_e32 v0, v1
	v_mov_b32_e32 v2, v1
	v_mov_b32_e32 v3, v1
	v_mov_b32_e32 v4, v1
	v_mov_b32_e32 v5, v1
	v_mov_b32_e32 v6, v1
	v_mov_b32_e32 v7, v1
	v_mov_b32_e32 v8, v1
	v_mov_b32_e32 v9, v1
	v_mov_b32_e32 v10, v1
	v_mov_b32_e32 v11, v1
	v_mov_b32_e32 v12, v1
	v_mov_b32_e32 v13, v1
	v_mov_b64_e32 v[30:31], v[14:15]
	v_mov_b64_e32 v[28:29], v[12:13]
	v_mov_b64_e32 v[26:27], v[10:11]
	v_mov_b64_e32 v[24:25], v[8:9]
	v_mov_b64_e32 v[22:23], v[6:7]
	v_mov_b64_e32 v[20:21], v[4:5]
	v_mov_b64_e32 v[18:19], v[2:3]
	v_mov_b64_e32 v[16:17], v[0:1]
	s_mov_b32 s41, 0
	s_cmp_lt_i32 s59, -3
	v_lshlrev_b32_e32 v157, 2, v33
	s_cbranch_scc1 .LBB0_137
	s_lshl_b32 s60, s8, 8
	s_add_i32 s56, s59, 4
	s_add_i32 s60, s60, 0x8000
	v_ashrrev_i32_e32 v38, 3, v32
	v_lshlrev_b32_e32 v39, 4, v32
	v_and_b32_e32 v34, 16, v32
	v_lshlrev_b32_e32 v35, 2, v32
	s_cmp_gt_i32 s59, 0
	v_lshlrev_b32_e32 v32, 10, v32
	s_cselect_b32 s0, s57, s60
	v_and_b32_e32 v174, 0x1000, v32
	v_or_b32_e32 v32, s22, v165
	v_and_or_b32 v34, v35, 12, v34
	v_lshlrev_b32_e32 v172, 8, v33
	v_add_u32_e32 v33, s0, v38
	v_sub_u32_e64 v32, v32, 8 clamp
	v_lshlrev_b32_e32 v171, 1, v34
	v_mad_i64_i32 v[34:35], s[0:1], s40, v33, 0
	v_min_u32_e32 v32, 48, v32
	v_or_b32_e32 v33, 1, v157
	v_lshlrev_b64 v[34:35], 1, v[34:35]
	s_movk_i32 s0, 0x90
	v_sub_u32_e32 v33, v33, v32
	v_lshl_add_u64 v[36:37], s[50:51], 0, v[34:35]
	v_and_b32_e32 v158, 0x70, v39
	v_mov_b32_e32 v159, v1
	v_lshl_add_u64 v[34:35], s[48:49], 0, v[34:35]
	v_mul_lo_u32 v173, v38, s0
	v_cmp_gt_u32_e64 s[0:1], 16, v33
	v_or_b32_e32 v33, 33, v157
	v_lshl_add_u64 v[34:35], v[34:35], 0, v[158:159]
	v_writelane_b32 v255, s0, 12
	v_sub_u32_e32 v33, v33, v32
	flat_load_dwordx4 v[150:153], v[34:35]
	v_or_b32_e32 v34, 2, v157
	v_writelane_b32 v255, s1, 13
	v_cmp_gt_u32_e64 s[0:1], 16, v33
	v_sub_u32_e32 v33, v34, v32
	v_or_b32_e32 v35, 3, v157
	v_writelane_b32 v255, s0, 14
	v_lshl_add_u64 v[36:37], v[36:37], 0, v[158:159]
	flat_load_dwordx4 v[146:149], v[36:37]
	v_writelane_b32 v255, s1, 15
	v_cmp_gt_u32_e64 s[0:1], 16, v33
	v_or_b32_e32 v33, 34, v157
	v_sub_u32_e32 v33, v33, v32
	v_writelane_b32 v255, s0, 16
	v_or_b32_e32 v36, 8, v157
	v_or_b32_e32 v37, 9, v157
	v_writelane_b32 v255, s1, 17
	v_cmp_gt_u32_e64 s[0:1], 16, v33
	v_sub_u32_e32 v33, v35, v32
	v_and_b32_e32 v65, 0xc0, v39
	v_writelane_b32 v255, s0, 18
	v_and_b32_e32 v176, 48, v39
	v_or_b32_e32 v39, 10, v157
	v_writelane_b32 v255, s1, 19
	v_cmp_gt_u32_e64 s[0:1], 16, v33
	v_or_b32_e32 v33, 35, v157
	v_sub_u32_e32 v33, v33, v32
	v_writelane_b32 v255, s0, 20
	v_or_b32_e32 v40, 11, v157
	v_or_b32_e32 v41, 16, v157
	v_writelane_b32 v255, s1, 21
	v_cmp_gt_u32_e64 s[0:1], 16, v33
	v_sub_u32_e32 v33, v36, v32
	v_or_b32_e32 v42, 17, v157
	v_writelane_b32 v255, s0, 22
	v_or_b32_e32 v43, 18, v157
	v_or_b32_e32 v44, 19, v157
	v_writelane_b32 v255, s1, 23
	v_cmp_gt_u32_e64 s[0:1], 16, v33
	v_or_b32_e32 v33, 40, v157
	v_sub_u32_e32 v33, v33, v32
	v_writelane_b32 v255, s0, 24
	v_or_b32_e32 v45, 24, v157
	s_mov_b64 s[68:69], s[92:93]
	v_writelane_b32 v255, s1, 25
	v_cmp_gt_u32_e64 s[0:1], 16, v33
	v_sub_u32_e32 v33, v37, v32
	v_or_b32_e32 v46, 25, v157
	v_writelane_b32 v255, s0, 26
	s_mov_b64 s[70:71], s[94:95]
	v_or_b32_e32 v47, 26, v157
	v_writelane_b32 v255, s1, 27
	v_cmp_gt_u32_e64 s[0:1], 16, v33
	v_or_b32_e32 v33, 41, v157
	v_sub_u32_e32 v33, v33, v32
	v_writelane_b32 v255, s0, 28
	s_mov_b64 s[64:65], s[98:99]
	v_or_b32_e32 v48, 27, v157
	v_writelane_b32 v255, s1, 29
	v_cmp_gt_u32_e64 s[0:1], 16, v33
	v_sub_u32_e32 v33, v39, v32
	v_sub_u32_e32 v49, v157, v32
	v_writelane_b32 v255, s0, 30
	v_cmp_gt_u32_e64 s[72:73], 16, v49
	v_or_b32_e32 v49, 32, v157
	v_writelane_b32 v255, s1, 31
	v_cmp_gt_u32_e64 s[0:1], 16, v33
	v_or_b32_e32 v33, 42, v157
	v_sub_u32_e32 v33, v33, v32
	v_writelane_b32 v255, s0, 32
	s_cmp_eq_u32 s53, 1
	v_sub_u32_e32 v49, v49, v32
	v_writelane_b32 v255, s1, 33
	v_cmp_gt_u32_e64 s[0:1], 16, v33
	v_sub_u32_e32 v33, v40, v32
	s_cselect_b64 s[84:85], -1, 0
	v_writelane_b32 v255, s0, 34
	s_add_i32 s58, s61, 8
	s_cmp_eq_u32 s53, 2
	v_writelane_b32 v255, s1, 35
	v_cmp_gt_u32_e64 s[0:1], 16, v33
	v_or_b32_e32 v33, 43, v157
	v_sub_u32_e32 v33, v33, v32
	v_writelane_b32 v255, s0, 36
	v_readlane_b32 s18, v254, 50
	v_lshl_add_u64 v[160:161], s[48:49], 0, v[158:159]
	v_writelane_b32 v255, s1, 37
	v_cmp_gt_u32_e64 s[0:1], 16, v33
	v_sub_u32_e32 v33, v41, v32
	v_lshl_add_u64 v[162:163], s[50:51], 0, v[158:159]
	v_writelane_b32 v255, s0, 38
	s_cselect_b64 s[86:87], -1, 0
	s_add_i32 s63, s52, 0xffffff9f
	v_writelane_b32 v255, s1, 39
	v_cmp_gt_u32_e64 s[0:1], 16, v33
	v_or_b32_e32 v33, 48, v157
	v_sub_u32_e32 v33, v33, v32
	v_writelane_b32 v255, s0, 40
	s_add_i32 s80, s52, 0x41
	v_lshlrev_b32_e32 v175, 6, v38
	v_writelane_b32 v255, s1, 41
	v_cmp_gt_u32_e64 s[0:1], 16, v33
	v_sub_u32_e32 v33, v42, v32
	v_cmp_gt_u32_e64 s[74:75], 16, v49
	v_writelane_b32 v255, s0, 42
	v_add_u32_e32 v211, 64, v38
	v_mul_u32_u24_e32 v177, 0x90, v165
	v_writelane_b32 v255, s1, 43
	v_cmp_gt_u32_e64 s[0:1], 16, v33
	v_or_b32_e32 v33, 49, v157
	v_sub_u32_e32 v33, v33, v32
	v_writelane_b32 v255, s0, 44
; template <int DQ>
; __device__ __forceinline__ void attn_unit(LAS unsigned char* lds, const AttnDesc& A, int tid_in, int wid, int lane_in) {
;     ...
;             if (loc && A.mode == 1) {
;                 const int qc = 32 * (wid & 1) + r32;
;                 const int w0 = min(max(qc - 8, 0), 48);
;                 const int rbase = (A.a0 + t - A.a1 + 7) * 31;
; #pragma unroll
;                 for (int r = 0; r < 16; ++r) {
;                     const int kc = (r & 3) + 8 * (r >> 2) + 4 * h;
;                     { const int dc = min(max(kc - qc + 15, 0), 30); const bool ok = (unsigned)(kc - w0) < 16u; const float bv = rpbl[rbase + dc]; s0[r] = ok ? s0[r] + bv : -1e30f; }
;                     { const int kc2 = kc + 32; const int dc = min(max(kc2 - qc + 15, 0), 30); const bool ok = (unsigned)(kc2 - w0) < 16u; const float bv = rpbl[rbase + dc]; s1[r] = ok ? s1[r] + bv : -1e30f; }
;                 }
	v_mov_b32_e32 v212, 0xf149f2ca
	v_mov_b32_e32 v213, 0xf149f2ca
	v_mov_b32_e32 v64, 0
	v_writelane_b32 v255, s1, 45
	v_cmp_gt_u32_e64 s[0:1], 16, v33
	v_sub_u32_e32 v33, v43, v32
	s_mov_b32 s82, 0
	v_writelane_b32 v255, s0, 46
	s_nop 1
	v_writelane_b32 v255, s1, 47
	v_cmp_gt_u32_e64 s[0:1], 16, v33
	v_or_b32_e32 v33, 50, v157
	v_sub_u32_e32 v33, v33, v32
	v_writelane_b32 v255, s0, 48
	s_nop 1
	v_writelane_b32 v255, s1, 49
	v_cmp_gt_u32_e64 s[0:1], 16, v33
	v_sub_u32_e32 v33, v44, v32
	v_cmp_gt_u32_e64 s[88:89], 16, v33
	v_or_b32_e32 v33, 51, v157
	v_sub_u32_e32 v33, v33, v32
	v_cmp_gt_u32_e64 s[90:91], 16, v33
	v_sub_u32_e32 v33, v45, v32
	v_cmp_gt_u32_e64 s[92:93], 16, v33
	v_or_b32_e32 v33, 56, v157
	v_sub_u32_e32 v33, v33, v32
	v_cmp_gt_u32_e64 s[94:95], 16, v33
	v_sub_u32_e32 v33, v46, v32
	v_cmp_gt_u32_e64 s[96:97], 16, v33
	v_or_b32_e32 v33, 57, v157
	v_sub_u32_e32 v33, v33, v32
	v_writelane_b32 v255, s0, 50
	v_cmp_gt_u32_e64 s[98:99], 16, v33
	v_sub_u32_e32 v33, v47, v32
	v_writelane_b32 v255, s1, 51
	v_cmp_gt_u32_e64 s[0:1], 16, v33
	v_or_b32_e32 v33, 58, v157
	v_sub_u32_e32 v33, v33, v32
	v_cmp_gt_u32_e64 s[4:5], 16, v33
	v_sub_u32_e32 v33, v48, v32
	v_cmp_gt_u32_e64 s[6:7], 16, v33
	v_or_b32_e32 v33, 59, v157
	v_sub_u32_e32 v32, v33, v32
	v_cmp_gt_u32_e64 s[8:9], 16, v32
	v_add_u32_e32 v32, s52, v165
	v_sub_u32_e32 v159, v157, v32
	v_add_u32_e32 v32, s18, v157
	s_mul_i32 s18, s55, 0x7c
	s_mulk_i32 s52, 0x7c
	v_sub_u32_e32 v32, v32, v165
	s_sub_i32 s18, s18, s52
	v_max_i32_e32 v32, -15, v32
	s_add_i32 s81, s18, 0
	v_readlane_b32 s18, v254, 51
	v_lshlrev_b32_e32 v178, 2, v32
	v_mov_b64_e32 v[62:63], v[14:15]
	v_add_u32_e32 v32, s18, v157
	v_sub_u32_e32 v32, v32, v165
	v_max_i32_e32 v32, -15, v32
	v_add_u32_e32 v32, 15, v32
	v_min_u32_e32 v32, 30, v32
	v_readlane_b32 s18, v254, 52
	v_lshlrev_b32_e32 v179, 2, v32
	v_mov_b64_e32 v[60:61], v[12:13]
	v_add_u32_e32 v32, s18, v157
	v_sub_u32_e32 v32, v32, v165
	v_max_i32_e32 v32, -15, v32
	v_readlane_b32 s18, v254, 53
	v_lshlrev_b32_e32 v180, 2, v32
	v_mov_b64_e32 v[58:59], v[10:11]
	v_add_u32_e32 v32, s18, v157
	v_sub_u32_e32 v32, v32, v165
	v_max_i32_e32 v32, -15, v32
	v_add_u32_e32 v32, 15, v32
	v_min_u32_e32 v32, 30, v32
	v_readlane_b32 s18, v254, 54
	v_lshlrev_b32_e32 v182, 2, v32
	v_mov_b64_e32 v[56:57], v[8:9]
	v_add_u32_e32 v32, s18, v157
	v_sub_u32_e32 v32, v32, v165
	v_max_i32_e32 v32, -15, v32
	v_readlane_b32 s18, v254, 55
	v_lshlrev_b32_e32 v183, 2, v32
	v_mov_b64_e32 v[54:55], v[6:7]
	v_add_u32_e32 v32, s18, v157
	v_sub_u32_e32 v32, v32, v165
	v_max_i32_e32 v32, -15, v32
	v_add_u32_e32 v32, 15, v32
	v_min_u32_e32 v32, 30, v32
	v_readlane_b32 s18, v254, 56
	v_lshlrev_b32_e32 v184, 2, v32
	v_mov_b64_e32 v[52:53], v[4:5]
	v_add_u32_e32 v32, s18, v157
	v_sub_u32_e32 v32, v32, v165
	v_max_i32_e32 v32, -15, v32
	v_readlane_b32 s18, v254, 57
	v_lshlrev_b32_e32 v185, 2, v32
	v_mov_b64_e32 v[50:51], v[2:3]
	v_add_u32_e32 v32, s18, v157
	v_sub_u32_e32 v32, v32, v165
	v_max_i32_e32 v32, -15, v32
	v_add_u32_e32 v32, 15, v32
	v_min_u32_e32 v32, 30, v32
	v_readlane_b32 s18, v254, 58
	v_lshlrev_b32_e32 v186, 2, v32
	v_mov_b64_e32 v[48:49], v[0:1]
	v_add_u32_e32 v32, s18, v157
	v_sub_u32_e32 v32, v32, v165
	v_max_i32_e32 v32, -15, v32
	v_readlane_b32 s18, v254, 59
	v_lshlrev_b32_e32 v187, 2, v32
	s_nop 0
	v_add_u32_e32 v32, s18, v157
	v_sub_u32_e32 v32, v32, v165
	v_max_i32_e32 v32, -15, v32
	v_add_u32_e32 v32, 15, v32
	v_min_u32_e32 v32, 30, v32
	v_readlane_b32 s18, v254, 60
	v_lshlrev_b32_e32 v188, 2, v32
	s_nop 0
	v_add_u32_e32 v32, s18, v157
	v_sub_u32_e32 v32, v32, v165
	v_max_i32_e32 v32, -15, v32
	v_readlane_b32 s18, v254, 61
	v_lshlrev_b32_e32 v189, 2, v32
	s_nop 0
	v_add_u32_e32 v32, s18, v157
	v_sub_u32_e32 v32, v32, v165
	v_max_i32_e32 v32, -15, v32
	v_add_u32_e32 v32, 15, v32
	v_min_u32_e32 v32, 30, v32
	v_readlane_b32 s18, v254, 62
	v_lshlrev_b32_e32 v190, 2, v32
	s_nop 0
	v_add_u32_e32 v32, s18, v157
	v_sub_u32_e32 v32, v32, v165
	v_max_i32_e32 v32, -15, v32
	v_readlane_b32 s18, v254, 63
	v_lshlrev_b32_e32 v191, 2, v32
	s_nop 0
	v_add_u32_e32 v32, s18, v157
	v_sub_u32_e32 v32, v32, v165
	v_max_i32_e32 v32, -15, v32
	v_add_u32_e32 v32, 15, v32
	v_min_u32_e32 v32, 30, v32
	v_readlane_b32 s18, v255, 0
	v_lshlrev_b32_e32 v192, 2, v32
	s_nop 0
	v_add_u32_e32 v32, s18, v157
	v_sub_u32_e32 v32, v32, v165
	v_max_i32_e32 v32, -15, v32
	v_readlane_b32 s18, v255, 1
	v_lshlrev_b32_e32 v193, 2, v32
	s_nop 0
	v_add_u32_e32 v32, s18, v157
	v_sub_u32_e32 v32, v32, v165
	v_max_i32_e32 v32, -15, v32
	v_add_u32_e32 v32, 15, v32
	v_min_u32_e32 v32, 30, v32
	v_readlane_b32 s18, v255, 2
	v_lshlrev_b32_e32 v194, 2, v32
	s_nop 0
	v_add_u32_e32 v32, s18, v157
	v_sub_u32_e32 v32, v32, v165
	v_max_i32_e32 v32, -15, v32
	v_add_u32_e32 v32, 15, v32
	v_min_u32_e32 v32, 30, v32
	v_readlane_b32 s18, v255, 3
	v_lshlrev_b32_e32 v195, 2, v32
	s_nop 0
	v_add_u32_e32 v32, s18, v157
	v_sub_u32_e32 v32, v32, v165
	v_min_u32_e32 v32, 30, v32
	v_readlane_b32 s18, v255, 4
	v_lshlrev_b32_e32 v196, 2, v32
	s_nop 0
	v_add_u32_e32 v32, s18, v157
	v_sub_u32_e32 v32, v32, v165
	v_max_i32_e32 v32, -15, v32
	v_add_u32_e32 v32, 15, v32
	v_min_u32_e32 v32, 30, v32
	v_readlane_b32 s18, v255, 5
	v_lshlrev_b32_e32 v197, 2, v32
	s_nop 0
; template <int DQ>
; __device__ __forceinline__ void attn_unit(LAS unsigned char* lds, const AttnDesc& A, int tid_in, int wid, int lane_in) {
;     ...
;     f32x16 o0, o1;
; #pragma unroll
;     for (int r = 0; r < 16; ++r) { o0[r] = 0.f; o1[r] = 0.f; }
;     ...
;             if (loc && A.mode == 1) {
;                 const int qc = 32 * (wid & 1) + r32;
;                 const int w0 = min(max(qc - 8, 0), 48);
;                 const int rbase = (A.a0 + t - A.a1 + 7) * 31;
; #pragma unroll
;                 for (int r = 0; r < 16; ++r) {
;                     const int kc = (r & 3) + 8 * (r >> 2) + 4 * h;
;                     { const int dc = min(max(kc - qc + 15, 0), 30); const bool ok = (unsigned)(kc - w0) < 16u; const float bv = rpbl[rbase + dc]; s0[r] = ok ? s0[r] + bv : -1e30f; }
;                     { const int kc2 = kc + 32; const int dc = min(max(kc2 - qc + 15, 0), 30); const bool ok = (unsigned)(kc2 - w0) < 16u; const float bv = rpbl[rbase + dc]; s1[r] = ok ? s1[r] + bv : -1e30f; }
;                 }
	v_add_u32_e32 v32, s18, v157
	v_sub_u32_e32 v32, v32, v165
	v_min_u32_e32 v32, 30, v32
	v_readlane_b32 s18, v255, 6
	v_lshlrev_b32_e32 v198, 2, v32
	s_nop 0
	v_add_u32_e32 v32, s18, v157
	v_sub_u32_e32 v32, v32, v165
	v_max_i32_e32 v32, -15, v32
	v_add_u32_e32 v32, 15, v32
	v_min_u32_e32 v32, 30, v32
	v_readlane_b32 s18, v255, 7
	v_lshlrev_b32_e32 v199, 2, v32
	s_nop 0
	v_add_u32_e32 v32, s18, v157
	v_sub_u32_e32 v32, v32, v165
	v_min_u32_e32 v32, 30, v32
	v_readlane_b32 s18, v255, 8
	v_lshlrev_b32_e32 v200, 2, v32
	s_nop 0
	v_add_u32_e32 v32, s18, v157
	v_sub_u32_e32 v32, v32, v165
	v_max_i32_e32 v32, -15, v32
	v_add_u32_e32 v32, 15, v32
	v_min_u32_e32 v32, 30, v32
	v_readlane_b32 s18, v255, 9
	v_lshlrev_b32_e32 v201, 2, v32
	s_nop 0
	v_add_u32_e32 v32, s18, v157
	v_sub_u32_e32 v32, v32, v165
	v_min_u32_e32 v32, 30, v32
	v_lshlrev_b32_e32 v202, 2, v32
	v_add_u32_e32 v32, s21, v157
	v_sub_u32_e32 v32, v32, v165
	v_max_i32_e32 v32, -15, v32
	v_add_u32_e32 v32, 15, v32
	v_min_u32_e32 v32, 30, v32
	v_lshlrev_b32_e32 v203, 2, v32
	v_add_u32_e32 v32, s23, v157
	v_sub_u32_e32 v32, v32, v165
	v_min_u32_e32 v32, 30, v32
	v_lshlrev_b32_e32 v204, 2, v32
	v_add_u32_e32 v32, s24, v157
	v_sub_u32_e32 v32, v32, v165
	v_max_i32_e32 v32, -15, v32
	v_add_u32_e32 v32, 15, v32
	v_min_u32_e32 v32, 30, v32
	v_lshlrev_b32_e32 v205, 2, v32
	v_add_u32_e32 v32, s25, v157
	v_sub_u32_e32 v32, v32, v165
	v_min_u32_e32 v32, 30, v32
	v_lshlrev_b32_e32 v206, 2, v32
	v_add_u32_e32 v32, s26, v157
	v_sub_u32_e32 v32, v32, v165
	v_max_i32_e32 v32, -15, v32
	v_add_u32_e32 v32, 15, v32
	v_min_u32_e32 v32, 30, v32
	v_lshlrev_b32_e32 v207, 2, v32
	v_add_u32_e32 v32, s27, v157
	v_sub_u32_e32 v32, v32, v165
	v_min_u32_e32 v32, 30, v32
	v_lshlrev_b32_e32 v208, 2, v32
	v_add_u32_e32 v32, s31, v157
	v_sub_u32_e32 v32, v32, v165
	v_max_i32_e32 v32, -15, v32
	v_add_u32_e32 v32, 15, v32
	v_min_u32_e32 v32, 30, v32
	v_lshlrev_b32_e32 v209, 2, v32
	v_add_u32_e32 v32, s46, v157
	v_sub_u32_e32 v32, v32, v165
	v_min_u32_e32 v32, 30, v32
	v_lshlrev_b32_e32 v210, 2, v32
	v_mov_b64_e32 v[46:47], v[14:15]
	v_mov_b64_e32 v[44:45], v[12:13]
	v_mov_b64_e32 v[42:43], v[10:11]
	v_mov_b64_e32 v[40:41], v[8:9]
	v_mov_b64_e32 v[38:39], v[6:7]
	v_mov_b64_e32 v[36:37], v[4:5]
	v_mov_b64_e32 v[34:35], v[2:3]
	v_mov_b64_e32 v[32:33], v[0:1]
	v_min_u32_e32 v0, 464, v236
	v_lshlrev_b32_e32 v0, 2, v0
	ds_write_b32 v0, v241 offset:44868
	v_mov_b32_e32 v2, 1800
	v_mov_b32_e32 v3, 1860
	v_cndmask_b32_e64 v178, v2, v178, s[72:73]
	v_cndmask_b32_e64 v179, v3, v179, s[74:75]
	v_readlane_b32 s50, v255, 12
	v_readlane_b32 s51, v255, 13
	s_nop 1
	v_cndmask_b32_e64 v180, v2, v180, s[50:51]
	v_readlane_b32 s50, v255, 14
	v_readlane_b32 s51, v255, 15
	s_nop 1
	v_cndmask_b32_e64 v182, v3, v182, s[50:51]
	v_readlane_b32 s50, v255, 16
	v_readlane_b32 s51, v255, 17
	s_nop 1
	v_cndmask_b32_e64 v183, v2, v183, s[50:51]
	v_readlane_b32 s50, v255, 18
	v_readlane_b32 s51, v255, 19
	s_nop 1
	v_cndmask_b32_e64 v184, v3, v184, s[50:51]
	v_readlane_b32 s50, v255, 20
	v_readlane_b32 s51, v255, 21
	s_nop 1
	v_cndmask_b32_e64 v185, v2, v185, s[50:51]
	v_readlane_b32 s50, v255, 22
	v_readlane_b32 s51, v255, 23
	s_nop 1
	v_cndmask_b32_e64 v186, v3, v186, s[50:51]
	v_readlane_b32 s50, v255, 24
	v_readlane_b32 s51, v255, 25
	s_nop 1
	v_cndmask_b32_e64 v187, v2, v187, s[50:51]
	v_readlane_b32 s50, v255, 26
	v_readlane_b32 s51, v255, 27
	s_nop 1
	v_cndmask_b32_e64 v188, v3, v188, s[50:51]
	v_readlane_b32 s50, v255, 28
	v_readlane_b32 s51, v255, 29
	s_nop 1
	v_cndmask_b32_e64 v189, v2, v189, s[50:51]
	v_readlane_b32 s50, v255, 30
	v_readlane_b32 s51, v255, 31
	s_nop 1
	v_cndmask_b32_e64 v190, v3, v190, s[50:51]
	v_readlane_b32 s50, v255, 32
	v_readlane_b32 s51, v255, 33
	s_nop 1
	v_cndmask_b32_e64 v191, v2, v191, s[50:51]
	v_readlane_b32 s50, v255, 34
	v_readlane_b32 s51, v255, 35
	s_nop 1
	v_cndmask_b32_e64 v192, v3, v192, s[50:51]
	v_readlane_b32 s50, v255, 36
	v_readlane_b32 s51, v255, 37
	s_nop 1
	v_cndmask_b32_e64 v193, v2, v193, s[50:51]
	v_readlane_b32 s50, v255, 38
	v_readlane_b32 s51, v255, 39
	s_nop 1
	v_cndmask_b32_e64 v194, v3, v194, s[50:51]
	v_readlane_b32 s50, v255, 40
	v_readlane_b32 s51, v255, 41
	s_nop 1
	v_cndmask_b32_e64 v195, v3, v195, s[50:51]
	v_readlane_b32 s50, v255, 42
	v_readlane_b32 s51, v255, 43
	s_nop 1
	v_cndmask_b32_e64 v196, v3, v196, s[50:51]
	v_readlane_b32 s50, v255, 44
	v_readlane_b32 s51, v255, 45
	s_nop 1
	v_cndmask_b32_e64 v197, v3, v197, s[50:51]
	v_readlane_b32 s50, v255, 46
	v_readlane_b32 s51, v255, 47
	s_nop 1
	v_cndmask_b32_e64 v198, v3, v198, s[50:51]
	v_readlane_b32 s50, v255, 48
	v_readlane_b32 s51, v255, 49
	s_nop 1
	v_cndmask_b32_e64 v199, v3, v199, s[50:51]
	v_readlane_b32 s50, v255, 50
	v_readlane_b32 s51, v255, 51
	s_nop 1
	v_cndmask_b32_e64 v200, v3, v200, s[50:51]
	v_cndmask_b32_e64 v201, v3, v201, s[88:89]
	v_cndmask_b32_e64 v202, v3, v202, s[90:91]
	v_cndmask_b32_e64 v203, v3, v203, s[92:93]
	v_cndmask_b32_e64 v204, v3, v204, s[94:95]
	v_cndmask_b32_e64 v205, v3, v205, s[96:97]
	v_cndmask_b32_e64 v206, v3, v206, s[98:99]
	v_cndmask_b32_e64 v207, v3, v207, s[0:1]
	v_cndmask_b32_e64 v208, v3, v208, s[4:5]
	v_cndmask_b32_e64 v209, v3, v209, s[6:7]
	v_cndmask_b32_e64 v210, v3, v210, s[8:9]

; #define LAS __attribute__((address_space(3)))
; __device__ __forceinline__ void attn_unit_mla(LAS unsigned char* lds, const AttnDesc& A, int tid_in, int wid, int lane_in) {
;     constexpr int KSTR = (96 + 8) * 2, NS = 6;
;     int tid = tid_in; asm volatile("" : "+v"(tid));
;     const int lane = tid & 63; (void)lane_in;
;     const int r32 = lane & 31, h = lane >> 5;
;     const int nt = A.nloc + 4, nstg = nt >> 1;
;     bf16x8 qf[NS];
; #pragma unroll
;     for (int s = 0; s < NS; ++s) qf[s] = *(const bf16x8*)(A.q + (size_t)r32 * A.ldq + 16 * s + 8 * h);
;     f32x16 o0, o1;
; #pragma unroll
;     for (int r = 0; r < 16; ++r) { o0[r] = 0.f; o1[r] = 0.f; }
;     float mrun = -1e30f, lrun = 0.f;
;     const int skey = tid >> 3, sch = tid & 7;
;     u32x4 ka, va, kra = (u32x4){0u, 0u, 0u, 0u}, kb_, vb_, krb = (u32x4){0u, 0u, 0u, 0u};
;     ...
;     MLA_LOAD(ka, va, kra, 0); MLA_LOAD(kb_, vb_, krb, 1);
.LBB0_145:
	s_add_i32 s4, s0, s11
	s_and_b32 s45, s1, 7
	s_mul_i32 s1, s4, 0x600
	s_mul_hi_i32 s0, s4, 0x600
	s_add_u32 s1, s66, s1
	s_addc_u32 s5, s67, s0
	s_mul_i32 s0, s45, 0xc0
	s_add_u32 s0, s1, s0
	s_addc_u32 s1, s5, 0
	v_mov_b32_e32 v6, v154
	s_lshl_b32 s5, s45, 8
	v_mov_b64_e32 v[2:3], s[0:1]
	v_and_b32_e32 v156, 31, v6
	s_movk_i32 s0, 0x600
	s_add_u32 s6, s76, s5
	v_mad_u64_u32 v[2:3], s[0:1], v156, s0, v[2:3]
	s_addc_u32 s7, s77, 0
	s_lshl_b32 s0, s41, 6
	v_bfe_u32 v157, v6, 5, 1
	s_sub_i32 s5, s40, s0
	v_lshlrev_b32_e32 v0, 4, v157
	s_and_b64 s[0:1], s[42:43], exec
	v_lshl_add_u64 v[2:3], v[2:3], 0, v[0:1]
	v_ashrrev_i32_e32 v171, 3, v6
	s_cselect_b32 s5, s44, s5
	flat_load_dwordx4 v[98:101], v[2:3]
	flat_load_dwordx4 v[102:105], v[2:3] offset:32
	flat_load_dwordx4 v[106:109], v[2:3] offset:64
	flat_load_dwordx4 v[110:113], v[2:3] offset:96
	flat_load_dwordx4 v[114:117], v[2:3] offset:128
	flat_load_dwordx4 v[118:121], v[2:3] offset:160
	v_add_u32_e32 v2, s5, v171
	v_ashrrev_i32_e32 v3, 31, v2
	v_and_b32_e32 v7, 7, v6
	v_lshlrev_b64 v[2:3], 11, v[2:3]
	v_lshl_add_u64 v[2:3], s[6:7], 0, v[2:3]
	v_lshlrev_b32_e32 v158, 4, v7
	v_mov_b32_e32 v159, v1
	v_lshl_add_u64 v[2:3], v[2:3], 0, v[158:159]
	flat_load_dwordx4 v[122:125], v[2:3]
	flat_load_dwordx4 v[126:129], v[2:3] offset:128
	s_movk_i32 s0, 0xff
	v_cmp_lt_i32_e32 vcc, s0, v6
	s_movk_i32 s0, 0x100
	v_lshlrev_b32_e32 v8, 4, v6
	v_cmp_gt_i32_e64 s[0:1], s0, v6
	v_mov_b32_e32 v130, v1
	v_mov_b32_e32 v131, v1
	v_mov_b32_e32 v132, v1
	v_mov_b32_e32 v133, v1
	v_ashrrev_i32_e32 v159, 2, v6
	v_and_b32_e32 v160, 48, v8
	s_and_saveexec_b64 s[8:9], s[0:1]
	s_cbranch_execz .LBB0_147
	v_ashrrev_i32_e32 v2, 2, v6
	v_add_u32_e32 v4, s5, v2
	v_mov_b64_e32 v[2:3], s[92:93]
	v_mad_i64_i32 v[2:3], s[18:19], v4, s90, v[2:3]
	v_mov_b32_e32 v161, v1
	v_lshl_add_u64 v[2:3], v[2:3], 0, v[160:161]
	flat_load_dwordx4 v[130:133], v[2:3]
